# residual epilogue rewritten: loads streamed with counted vmcnt, stores as ready, batched cross-lane reduction of row sums of squares
# speedup vs baseline: 1.0057x; 1.0057x over previous
; __device__ __forceinline__ unsigned cvt_pk_bf16(float lo, float hi) { unsigned r; asm volatile("v_cvt_pk_bf16_f32 %0, %1, %2" : "=v"(r) : "v"(lo), "v"(hi)); return r; }
;     __device__ __forceinline__ void operator()(const f32x4 (&acc)[2][2][4][2], const Unit& u, int wr, int wc, int fr, int fq) const {
;     ...
;         u32x4 bb[2][4][2];
; #pragma unroll
;         for (int ai = 0; ai < 2; ++ai)
; #pragma unroll
;             for (int m = 0; m < 4; ++m)
; #pragma unroll
;                 for (int bj = 0; bj < 2; ++bj) bb[ai][m][bj] = *(const u32x4*)(xb + (size_t)(row0 + ai * HALF + m * 16) * D + col0 + bj * HALF);
; #pragma unroll
;         for (int ai = 0; ai < 2; ++ai)
; #pragma unroll
;             for (int m = 0; m < 4; ++m) { const size_t off = (size_t)(row0 + ai * HALF + m * 16) * D + col0; float sq = 0.f;
; #pragma unroll
;                 for (int bj = 0; bj < 2; ++bj) { const u32x4 b = bb[ai][m][bj];
;                     const f32x4 v0 = acc[ai][bj][m][0] + (f32x4){bflo(b.x), bfhi(b.x), bflo(b.y), bfhi(b.y)}, v1 = acc[ai][bj][m][1] + (f32x4){bflo(b.z), bfhi(b.z), bflo(b.w), bfhi(b.w)};
;                     u32x4 w; w.x = cvt_pk_bf16(v0[0], v0[1]); w.y = cvt_pk_bf16(v0[2], v0[3]); w.z = cvt_pk_bf16(v1[0], v1[1]); w.w = cvt_pk_bf16(v1[2], v1[3]);
;                     *(u32x4*)(xb + off + bj * HALF) = w;
;                     const float r0 = bflo(w.x), r1 = bfhi(w.x), r2 = bflo(w.y), r3 = bfhi(w.y), r4 = bflo(w.z), r5 = bfhi(w.z), r6 = bflo(w.w), r7 = bfhi(w.w);
;                     sq += ((r0 * r0 + r1 * r1) + (r2 * r2 + r3 * r3)) + ((r4 * r4 + r5 * r5) + (r6 * r6 + r7 * r7)); }
.LBB0_154:
	s_lshl_b32 s35, s35, 8
	v_add_u32_e32 v207, s35, v242
	v_lshl_or_b32 v206, s34, 8, v243
	v_lshlrev_b32_e32 v207, 11, v207
	v_lshl_add_u32 v207, v206, 1, v207
	s_mov_b32 s4, 0xffff0000
	v_mov_b32_e32 v206, v207
	global_load_dwordx4 v[108:111], v207, s[18:19]
	global_load_dwordx4 v[120:123], v207, s[18:19] offset:256
	v_add_u32_e32 v207, 0x8000, v207
	global_load_dwordx4 v[128:131], v207, s[18:19]
	global_load_dwordx4 v[132:135], v207, s[18:19] offset:256
	v_add_u32_e32 v207, 0x8000, v207
	global_load_dwordx4 v[136:139], v207, s[18:19]
	global_load_dwordx4 v[144:147], v207, s[18:19] offset:256
	v_add_u32_e32 v207, 0x8000, v207
	global_load_dwordx4 v[148:151], v207, s[18:19]
	global_load_dwordx4 v[152:155], v207, s[18:19] offset:256
	v_add_u32_e32 v207, 0x28000, v207
	global_load_dwordx4 v[156:159], v207, s[18:19]
	global_load_dwordx4 v[160:163], v207, s[18:19] offset:256
	v_add_u32_e32 v207, 0x8000, v207
	global_load_dwordx4 v[164:167], v207, s[18:19]
	global_load_dwordx4 v[176:179], v207, s[18:19] offset:256
	v_add_u32_e32 v207, 0x8000, v207
	global_load_dwordx4 v[180:183], v207, s[18:19]
	global_load_dwordx4 v[184:187], v207, s[18:19] offset:256
	v_add_u32_e32 v207, 0x8000, v207
	global_load_dwordx4 v[188:191], v207, s[18:19]
	global_load_dwordx4 v[202:205], v207, s[18:19] offset:256
	v_mov_b32_e32 v216, 0
	v_mov_b32_e32 v217, 0
	v_mov_b32_e32 v218, 0
	v_mov_b32_e32 v219, 0
	v_mov_b32_e32 v248, 0
	v_mov_b32_e32 v249, 0
	v_mov_b32_e32 v250, 0
	v_mov_b32_e32 v251, 0
	v_mov_b32_e32 v252, 0
	v_mov_b32_e32 v253, 0
	v_mov_b32_e32 v2, 0
	v_mov_b32_e32 v3, 0
	v_mov_b32_e32 v192, 0
	v_mov_b32_e32 v193, 0
	s_waitcnt vmcnt(14)
	v_lshlrev_b32_e32 v208, 16, v108
	v_and_b32_e32 v209, s4, v108
	v_pk_add_f32 v[172:173], v[172:173], v[208:209]
	v_cvt_pk_bf16_f32 v108, v172, v173
	v_lshlrev_b32_e32 v212, 16, v108
	v_and_b32_e32 v213, s4, v108
	v_pk_fma_f32 v[216:217], v[212:213], v[212:213], v[216:217]
	v_lshlrev_b32_e32 v210, 16, v109
	v_and_b32_e32 v211, s4, v109
	v_pk_add_f32 v[174:175], v[174:175], v[210:211]
	v_cvt_pk_bf16_f32 v109, v174, v175
	v_lshlrev_b32_e32 v214, 16, v109
	v_and_b32_e32 v215, s4, v109
	v_pk_fma_f32 v[216:217], v[214:215], v[214:215], v[216:217]
	v_lshlrev_b32_e32 v208, 16, v110
	v_and_b32_e32 v209, s4, v110
	v_pk_add_f32 v[168:169], v[168:169], v[208:209]
	v_cvt_pk_bf16_f32 v110, v168, v169
	v_lshlrev_b32_e32 v212, 16, v110
	v_and_b32_e32 v213, s4, v110
	v_pk_fma_f32 v[216:217], v[212:213], v[212:213], v[216:217]
	v_lshlrev_b32_e32 v210, 16, v111
	v_and_b32_e32 v211, s4, v111
	v_pk_add_f32 v[170:171], v[170:171], v[210:211]
	v_cvt_pk_bf16_f32 v111, v170, v171
	v_lshlrev_b32_e32 v214, 16, v111
	v_and_b32_e32 v215, s4, v111
	v_pk_fma_f32 v[216:217], v[214:215], v[214:215], v[216:217]
	global_store_dwordx4 v206, v[108:111], s[18:19]
	v_lshlrev_b32_e32 v208, 16, v120
	v_and_b32_e32 v209, s4, v120
	v_pk_add_f32 v[140:141], v[140:141], v[208:209]
	v_cvt_pk_bf16_f32 v120, v140, v141
	v_lshlrev_b32_e32 v212, 16, v120
	v_and_b32_e32 v213, s4, v120
	v_pk_fma_f32 v[216:217], v[212:213], v[212:213], v[216:217]
	v_lshlrev_b32_e32 v210, 16, v121
	v_and_b32_e32 v211, s4, v121
	v_pk_add_f32 v[142:143], v[142:143], v[210:211]
	v_cvt_pk_bf16_f32 v121, v142, v143
	v_lshlrev_b32_e32 v214, 16, v121
	v_and_b32_e32 v215, s4, v121
	v_pk_fma_f32 v[216:217], v[214:215], v[214:215], v[216:217]
	v_lshlrev_b32_e32 v208, 16, v122
	v_and_b32_e32 v209, s4, v122
	v_pk_add_f32 v[124:125], v[124:125], v[208:209]
	v_cvt_pk_bf16_f32 v122, v124, v125
	v_lshlrev_b32_e32 v212, 16, v122
	v_and_b32_e32 v213, s4, v122
	v_pk_fma_f32 v[216:217], v[212:213], v[212:213], v[216:217]
	v_lshlrev_b32_e32 v210, 16, v123
	v_and_b32_e32 v211, s4, v123
	v_pk_add_f32 v[126:127], v[126:127], v[210:211]
	v_cvt_pk_bf16_f32 v123, v126, v127
	v_lshlrev_b32_e32 v214, 16, v123
	v_and_b32_e32 v215, s4, v123
	v_pk_fma_f32 v[216:217], v[214:215], v[214:215], v[216:217]
	global_store_dwordx4 v206, v[120:123], s[18:19] offset:256
	v_add_u32_e32 v206, 0x8000, v206
	s_waitcnt vmcnt(14)
	v_mov_b32_e32 v172, 0
	v_mov_b32_e32 v173, 0
	v_lshlrev_b32_e32 v208, 16, v128
	v_and_b32_e32 v209, s4, v128
	v_pk_add_f32 v[116:117], v[116:117], v[208:209]
	v_cvt_pk_bf16_f32 v128, v116, v117
	v_lshlrev_b32_e32 v212, 16, v128
	v_and_b32_e32 v213, s4, v128
	v_pk_fma_f32 v[218:219], v[212:213], v[212:213], v[218:219]
	v_lshlrev_b32_e32 v210, 16, v129
	v_and_b32_e32 v211, s4, v129
	v_pk_add_f32 v[118:119], v[118:119], v[210:211]
	v_cvt_pk_bf16_f32 v129, v118, v119
	v_lshlrev_b32_e32 v214, 16, v129
	v_and_b32_e32 v215, s4, v129
	v_pk_fma_f32 v[218:219], v[214:215], v[214:215], v[218:219]
	v_lshlrev_b32_e32 v208, 16, v130
	v_and_b32_e32 v209, s4, v130
	v_pk_add_f32 v[112:113], v[112:113], v[208:209]
	v_cvt_pk_bf16_f32 v130, v112, v113
	v_lshlrev_b32_e32 v212, 16, v130
	v_and_b32_e32 v213, s4, v130
	v_pk_fma_f32 v[218:219], v[212:213], v[212:213], v[218:219]
	v_lshlrev_b32_e32 v210, 16, v131
	v_and_b32_e32 v211, s4, v131
	v_pk_add_f32 v[114:115], v[114:115], v[210:211]
	v_cvt_pk_bf16_f32 v131, v114, v115
	v_lshlrev_b32_e32 v214, 16, v131
	v_and_b32_e32 v215, s4, v131
	v_pk_fma_f32 v[218:219], v[214:215], v[214:215], v[218:219]
	global_store_dwordx4 v206, v[128:131], s[18:19]
	v_lshlrev_b32_e32 v208, 16, v132
	v_and_b32_e32 v209, s4, v132
	v_pk_add_f32 v[104:105], v[104:105], v[208:209]
	v_cvt_pk_bf16_f32 v132, v104, v105
	v_lshlrev_b32_e32 v212, 16, v132
	v_and_b32_e32 v213, s4, v132
	v_pk_fma_f32 v[218:219], v[212:213], v[212:213], v[218:219]
	v_lshlrev_b32_e32 v210, 16, v133
	v_and_b32_e32 v211, s4, v133
	v_pk_add_f32 v[106:107], v[106:107], v[210:211]
	v_cvt_pk_bf16_f32 v133, v106, v107
	v_lshlrev_b32_e32 v214, 16, v133
	v_and_b32_e32 v215, s4, v133
	v_pk_fma_f32 v[218:219], v[214:215], v[214:215], v[218:219]
	v_lshlrev_b32_e32 v208, 16, v134
	v_and_b32_e32 v209, s4, v134
	v_pk_add_f32 v[100:101], v[100:101], v[208:209]
	v_cvt_pk_bf16_f32 v134, v100, v101
	v_lshlrev_b32_e32 v212, 16, v134
	v_and_b32_e32 v213, s4, v134
	v_pk_fma_f32 v[218:219], v[212:213], v[212:213], v[218:219]
	v_lshlrev_b32_e32 v210, 16, v135
	v_and_b32_e32 v211, s4, v135
	v_pk_add_f32 v[102:103], v[102:103], v[210:211]
	v_cvt_pk_bf16_f32 v135, v102, v103
	v_lshlrev_b32_e32 v214, 16, v135
	v_and_b32_e32 v215, s4, v135
	v_pk_fma_f32 v[218:219], v[214:215], v[214:215], v[218:219]
	global_store_dwordx4 v206, v[132:135], s[18:19] offset:256
	v_add_u32_e32 v206, 0x8000, v206
	s_waitcnt vmcnt(14)
; __device__ __forceinline__ unsigned cvt_pk_bf16(float lo, float hi) { unsigned r; asm volatile("v_cvt_pk_bf16_f32 %0, %1, %2" : "=v"(r) : "v"(lo), "v"(hi)); return r; }
;     __device__ __forceinline__ void operator()(const f32x4 (&acc)[2][2][4][2], const Unit& u, int wr, int wc, int fr, int fq) const {
;     ...
;         for (int ai = 0; ai < 2; ++ai)
; #pragma unroll
;             for (int m = 0; m < 4; ++m) { const size_t off = (size_t)(row0 + ai * HALF + m * 16) * D + col0; float sq = 0.f;
; #pragma unroll
;                 for (int bj = 0; bj < 2; ++bj) { const u32x4 b = bb[ai][m][bj];
;                     const f32x4 v0 = acc[ai][bj][m][0] + (f32x4){bflo(b.x), bfhi(b.x), bflo(b.y), bfhi(b.y)}, v1 = acc[ai][bj][m][1] + (f32x4){bflo(b.z), bfhi(b.z), bflo(b.w), bfhi(b.w)};
;                     u32x4 w; w.x = cvt_pk_bf16(v0[0], v0[1]); w.y = cvt_pk_bf16(v0[2], v0[3]); w.z = cvt_pk_bf16(v1[0], v1[1]); w.w = cvt_pk_bf16(v1[2], v1[3]);
;                     *(u32x4*)(xb + off + bj * HALF) = w;
;                     const float r0 = bflo(w.x), r1 = bfhi(w.x), r2 = bflo(w.y), r3 = bfhi(w.y), r4 = bflo(w.z), r5 = bfhi(w.z), r6 = bflo(w.w), r7 = bfhi(w.w);
;                     sq += ((r0 * r0 + r1 * r1) + (r2 * r2 + r3 * r3)) + ((r4 * r4 + r5 * r5) + (r6 * r6 + r7 * r7)); }
	v_lshlrev_b32_e32 v208, 16, v136
	v_and_b32_e32 v209, s4, v136
	v_pk_add_f32 v[96:97], v[96:97], v[208:209]
	v_cvt_pk_bf16_f32 v136, v96, v97
	v_lshlrev_b32_e32 v212, 16, v136
	v_and_b32_e32 v213, s4, v136
	v_pk_fma_f32 v[248:249], v[212:213], v[212:213], v[248:249]
	v_lshlrev_b32_e32 v210, 16, v137
	v_and_b32_e32 v211, s4, v137
	v_pk_add_f32 v[98:99], v[98:99], v[210:211]
	v_cvt_pk_bf16_f32 v137, v98, v99
	v_lshlrev_b32_e32 v214, 16, v137
	v_and_b32_e32 v215, s4, v137
	v_pk_fma_f32 v[248:249], v[214:215], v[214:215], v[248:249]
	v_lshlrev_b32_e32 v208, 16, v138
	v_and_b32_e32 v209, s4, v138
	v_pk_add_f32 v[92:93], v[92:93], v[208:209]
	v_cvt_pk_bf16_f32 v138, v92, v93
	v_lshlrev_b32_e32 v212, 16, v138
	v_and_b32_e32 v213, s4, v138
	v_pk_fma_f32 v[248:249], v[212:213], v[212:213], v[248:249]
	v_lshlrev_b32_e32 v210, 16, v139
	v_and_b32_e32 v211, s4, v139
	v_pk_add_f32 v[94:95], v[94:95], v[210:211]
	v_cvt_pk_bf16_f32 v139, v94, v95
	v_lshlrev_b32_e32 v214, 16, v139
	v_and_b32_e32 v215, s4, v139
	v_pk_fma_f32 v[248:249], v[214:215], v[214:215], v[248:249]
	global_store_dwordx4 v206, v[136:139], s[18:19]
	v_lshlrev_b32_e32 v208, 16, v144
	v_and_b32_e32 v209, s4, v144
	v_pk_add_f32 v[88:89], v[88:89], v[208:209]
	v_cvt_pk_bf16_f32 v144, v88, v89
	v_lshlrev_b32_e32 v212, 16, v144
	v_and_b32_e32 v213, s4, v144
	v_pk_fma_f32 v[248:249], v[212:213], v[212:213], v[248:249]
	v_lshlrev_b32_e32 v210, 16, v145
	v_and_b32_e32 v211, s4, v145
	v_pk_add_f32 v[90:91], v[90:91], v[210:211]
	v_cvt_pk_bf16_f32 v145, v90, v91
	v_lshlrev_b32_e32 v214, 16, v145
	v_and_b32_e32 v215, s4, v145
	v_pk_fma_f32 v[248:249], v[214:215], v[214:215], v[248:249]
	v_lshlrev_b32_e32 v208, 16, v146
	v_and_b32_e32 v209, s4, v146
	v_pk_add_f32 v[84:85], v[84:85], v[208:209]
	v_cvt_pk_bf16_f32 v146, v84, v85
	v_lshlrev_b32_e32 v212, 16, v146
	v_and_b32_e32 v213, s4, v146
	v_pk_fma_f32 v[248:249], v[212:213], v[212:213], v[248:249]
	v_lshlrev_b32_e32 v210, 16, v147
	v_and_b32_e32 v211, s4, v147
	v_pk_add_f32 v[86:87], v[86:87], v[210:211]
	v_cvt_pk_bf16_f32 v147, v86, v87
	v_lshlrev_b32_e32 v214, 16, v147
	v_and_b32_e32 v215, s4, v147
	v_pk_fma_f32 v[248:249], v[214:215], v[214:215], v[248:249]
	global_store_dwordx4 v206, v[144:147], s[18:19] offset:256
	v_add_u32_e32 v206, 0x8000, v206
	s_waitcnt vmcnt(14)
	v_lshlrev_b32_e32 v208, 16, v148
	v_and_b32_e32 v209, s4, v148
	v_pk_add_f32 v[80:81], v[80:81], v[208:209]
	v_cvt_pk_bf16_f32 v148, v80, v81
	v_lshlrev_b32_e32 v212, 16, v148
	v_and_b32_e32 v213, s4, v148
	v_pk_fma_f32 v[250:251], v[212:213], v[212:213], v[250:251]
	v_lshlrev_b32_e32 v210, 16, v149
	v_and_b32_e32 v211, s4, v149
	v_pk_add_f32 v[82:83], v[82:83], v[210:211]
	v_cvt_pk_bf16_f32 v149, v82, v83
	v_lshlrev_b32_e32 v214, 16, v149
	v_and_b32_e32 v215, s4, v149
	v_pk_fma_f32 v[250:251], v[214:215], v[214:215], v[250:251]
	v_lshlrev_b32_e32 v208, 16, v150
	v_and_b32_e32 v209, s4, v150
	v_pk_add_f32 v[76:77], v[76:77], v[208:209]
	v_cvt_pk_bf16_f32 v150, v76, v77
	v_lshlrev_b32_e32 v212, 16, v150
	v_and_b32_e32 v213, s4, v150
	v_pk_fma_f32 v[250:251], v[212:213], v[212:213], v[250:251]
	v_lshlrev_b32_e32 v210, 16, v151
	v_and_b32_e32 v211, s4, v151
	v_pk_add_f32 v[78:79], v[78:79], v[210:211]
	v_cvt_pk_bf16_f32 v151, v78, v79
	v_lshlrev_b32_e32 v214, 16, v151
	v_and_b32_e32 v215, s4, v151
	v_pk_fma_f32 v[250:251], v[214:215], v[214:215], v[250:251]
	global_store_dwordx4 v206, v[148:151], s[18:19]
	v_lshlrev_b32_e32 v208, 16, v152
	v_and_b32_e32 v209, s4, v152
	v_pk_add_f32 v[72:73], v[72:73], v[208:209]
	v_cvt_pk_bf16_f32 v152, v72, v73
	v_lshlrev_b32_e32 v212, 16, v152
	v_and_b32_e32 v213, s4, v152
	v_pk_fma_f32 v[250:251], v[212:213], v[212:213], v[250:251]
	v_lshlrev_b32_e32 v210, 16, v153
	v_and_b32_e32 v211, s4, v153
	v_pk_add_f32 v[74:75], v[74:75], v[210:211]
	v_cvt_pk_bf16_f32 v153, v74, v75
	v_lshlrev_b32_e32 v214, 16, v153
	v_and_b32_e32 v215, s4, v153
	v_pk_fma_f32 v[250:251], v[214:215], v[214:215], v[250:251]
	v_lshlrev_b32_e32 v208, 16, v154
	v_and_b32_e32 v209, s4, v154
	v_pk_add_f32 v[68:69], v[68:69], v[208:209]
	v_cvt_pk_bf16_f32 v154, v68, v69
	v_lshlrev_b32_e32 v212, 16, v154
	v_and_b32_e32 v213, s4, v154
	v_pk_fma_f32 v[250:251], v[212:213], v[212:213], v[250:251]
	v_lshlrev_b32_e32 v210, 16, v155
	v_and_b32_e32 v211, s4, v155
	v_pk_add_f32 v[70:71], v[70:71], v[210:211]
	v_cvt_pk_bf16_f32 v155, v70, v71
	v_lshlrev_b32_e32 v214, 16, v155
	v_and_b32_e32 v215, s4, v155
	v_pk_fma_f32 v[250:251], v[214:215], v[214:215], v[250:251]
	global_store_dwordx4 v206, v[152:155], s[18:19] offset:256
	v_add_u32_e32 v206, 0x28000, v206
	s_waitcnt vmcnt(14)
; __device__ __forceinline__ unsigned cvt_pk_bf16(float lo, float hi) { unsigned r; asm volatile("v_cvt_pk_bf16_f32 %0, %1, %2" : "=v"(r) : "v"(lo), "v"(hi)); return r; }
;     __device__ __forceinline__ void operator()(const f32x4 (&acc)[2][2][4][2], const Unit& u, int wr, int wc, int fr, int fq) const {
;     ...
;         for (int ai = 0; ai < 2; ++ai)
; #pragma unroll
;             for (int m = 0; m < 4; ++m) { const size_t off = (size_t)(row0 + ai * HALF + m * 16) * D + col0; float sq = 0.f;
; #pragma unroll
;                 for (int bj = 0; bj < 2; ++bj) { const u32x4 b = bb[ai][m][bj];
;                     const f32x4 v0 = acc[ai][bj][m][0] + (f32x4){bflo(b.x), bfhi(b.x), bflo(b.y), bfhi(b.y)}, v1 = acc[ai][bj][m][1] + (f32x4){bflo(b.z), bfhi(b.z), bflo(b.w), bfhi(b.w)};
;                     u32x4 w; w.x = cvt_pk_bf16(v0[0], v0[1]); w.y = cvt_pk_bf16(v0[2], v0[3]); w.z = cvt_pk_bf16(v1[0], v1[1]); w.w = cvt_pk_bf16(v1[2], v1[3]);
;                     *(u32x4*)(xb + off + bj * HALF) = w;
;                     const float r0 = bflo(w.x), r1 = bfhi(w.x), r2 = bflo(w.y), r3 = bfhi(w.y), r4 = bflo(w.z), r5 = bfhi(w.z), r6 = bflo(w.w), r7 = bfhi(w.w);
;                     sq += ((r0 * r0 + r1 * r1) + (r2 * r2 + r3 * r3)) + ((r4 * r4 + r5 * r5) + (r6 * r6 + r7 * r7)); }
	v_lshlrev_b32_e32 v208, 16, v156
	v_and_b32_e32 v209, s4, v156
	v_pk_add_f32 v[64:65], v[64:65], v[208:209]
	v_cvt_pk_bf16_f32 v156, v64, v65
	v_lshlrev_b32_e32 v212, 16, v156
	v_and_b32_e32 v213, s4, v156
	v_pk_fma_f32 v[252:253], v[212:213], v[212:213], v[252:253]
	v_lshlrev_b32_e32 v210, 16, v157
	v_and_b32_e32 v211, s4, v157
	v_pk_add_f32 v[66:67], v[66:67], v[210:211]
	v_cvt_pk_bf16_f32 v157, v66, v67
	v_lshlrev_b32_e32 v214, 16, v157
	v_and_b32_e32 v215, s4, v157
	v_pk_fma_f32 v[252:253], v[214:215], v[214:215], v[252:253]
	v_lshlrev_b32_e32 v208, 16, v158
	v_and_b32_e32 v209, s4, v158
	v_pk_add_f32 v[60:61], v[60:61], v[208:209]
	v_cvt_pk_bf16_f32 v158, v60, v61
	v_lshlrev_b32_e32 v212, 16, v158
	v_and_b32_e32 v213, s4, v158
	v_pk_fma_f32 v[252:253], v[212:213], v[212:213], v[252:253]
	v_lshlrev_b32_e32 v210, 16, v159
	v_and_b32_e32 v211, s4, v159
	v_pk_add_f32 v[62:63], v[62:63], v[210:211]
	v_cvt_pk_bf16_f32 v159, v62, v63
	v_lshlrev_b32_e32 v214, 16, v159
	v_and_b32_e32 v215, s4, v159
	v_pk_fma_f32 v[252:253], v[214:215], v[214:215], v[252:253]
	global_store_dwordx4 v206, v[156:159], s[18:19]
	v_lshlrev_b32_e32 v208, 16, v160
	v_and_b32_e32 v209, s4, v160
	v_pk_add_f32 v[56:57], v[56:57], v[208:209]
	v_cvt_pk_bf16_f32 v160, v56, v57
	v_lshlrev_b32_e32 v212, 16, v160
	v_and_b32_e32 v213, s4, v160
	v_pk_fma_f32 v[252:253], v[212:213], v[212:213], v[252:253]
	v_lshlrev_b32_e32 v210, 16, v161
	v_and_b32_e32 v211, s4, v161
	v_pk_add_f32 v[58:59], v[58:59], v[210:211]
	v_cvt_pk_bf16_f32 v161, v58, v59
	v_lshlrev_b32_e32 v214, 16, v161
	v_and_b32_e32 v215, s4, v161
	v_pk_fma_f32 v[252:253], v[214:215], v[214:215], v[252:253]
	v_lshlrev_b32_e32 v208, 16, v162
	v_and_b32_e32 v209, s4, v162
	v_pk_add_f32 v[52:53], v[52:53], v[208:209]
	v_cvt_pk_bf16_f32 v162, v52, v53
	v_lshlrev_b32_e32 v212, 16, v162
	v_and_b32_e32 v213, s4, v162
	v_pk_fma_f32 v[252:253], v[212:213], v[212:213], v[252:253]
	v_lshlrev_b32_e32 v210, 16, v163
	v_and_b32_e32 v211, s4, v163
	v_pk_add_f32 v[54:55], v[54:55], v[210:211]
	v_cvt_pk_bf16_f32 v163, v54, v55
	v_lshlrev_b32_e32 v214, 16, v163
	v_and_b32_e32 v215, s4, v163
	v_pk_fma_f32 v[252:253], v[214:215], v[214:215], v[252:253]
	global_store_dwordx4 v206, v[160:163], s[18:19] offset:256
	v_add_u32_e32 v206, 0x8000, v206
	s_waitcnt vmcnt(14)
	v_lshlrev_b32_e32 v208, 16, v164
	v_and_b32_e32 v209, s4, v164
	v_pk_add_f32 v[48:49], v[48:49], v[208:209]
	v_cvt_pk_bf16_f32 v164, v48, v49
	v_lshlrev_b32_e32 v212, 16, v164
	v_and_b32_e32 v213, s4, v164
	v_pk_fma_f32 v[2:3], v[212:213], v[212:213], v[2:3]
	v_lshlrev_b32_e32 v210, 16, v165
	v_and_b32_e32 v211, s4, v165
	v_pk_add_f32 v[50:51], v[50:51], v[210:211]
	v_cvt_pk_bf16_f32 v165, v50, v51
	v_lshlrev_b32_e32 v214, 16, v165
	v_and_b32_e32 v215, s4, v165
	v_pk_fma_f32 v[2:3], v[214:215], v[214:215], v[2:3]
	v_lshlrev_b32_e32 v208, 16, v166
	v_and_b32_e32 v209, s4, v166
	v_pk_add_f32 v[44:45], v[44:45], v[208:209]
	v_cvt_pk_bf16_f32 v166, v44, v45
	v_lshlrev_b32_e32 v212, 16, v166
	v_and_b32_e32 v213, s4, v166
	v_pk_fma_f32 v[2:3], v[212:213], v[212:213], v[2:3]
	v_lshlrev_b32_e32 v210, 16, v167
	v_and_b32_e32 v211, s4, v167
	v_pk_add_f32 v[46:47], v[46:47], v[210:211]
	v_cvt_pk_bf16_f32 v167, v46, v47
	v_lshlrev_b32_e32 v214, 16, v167
	v_and_b32_e32 v215, s4, v167
	v_pk_fma_f32 v[2:3], v[214:215], v[214:215], v[2:3]
	global_store_dwordx4 v206, v[164:167], s[18:19]
	v_lshlrev_b32_e32 v208, 16, v176
	v_and_b32_e32 v209, s4, v176
	v_pk_add_f32 v[40:41], v[40:41], v[208:209]
	v_cvt_pk_bf16_f32 v176, v40, v41
	v_lshlrev_b32_e32 v212, 16, v176
	v_and_b32_e32 v213, s4, v176
	v_pk_fma_f32 v[2:3], v[212:213], v[212:213], v[2:3]
	v_lshlrev_b32_e32 v210, 16, v177
	v_and_b32_e32 v211, s4, v177
	v_pk_add_f32 v[42:43], v[42:43], v[210:211]
	v_cvt_pk_bf16_f32 v177, v42, v43
	v_lshlrev_b32_e32 v214, 16, v177
	v_and_b32_e32 v215, s4, v177
	v_pk_fma_f32 v[2:3], v[214:215], v[214:215], v[2:3]
	v_lshlrev_b32_e32 v208, 16, v178
	v_and_b32_e32 v209, s4, v178
	v_pk_add_f32 v[36:37], v[36:37], v[208:209]
	v_cvt_pk_bf16_f32 v178, v36, v37
	v_lshlrev_b32_e32 v212, 16, v178
	v_and_b32_e32 v213, s4, v178
	v_pk_fma_f32 v[2:3], v[212:213], v[212:213], v[2:3]
	v_lshlrev_b32_e32 v210, 16, v179
	v_and_b32_e32 v211, s4, v179
	v_pk_add_f32 v[38:39], v[38:39], v[210:211]
	v_cvt_pk_bf16_f32 v179, v38, v39
	v_lshlrev_b32_e32 v214, 16, v179
	v_and_b32_e32 v215, s4, v179
	v_pk_fma_f32 v[2:3], v[214:215], v[214:215], v[2:3]
	global_store_dwordx4 v206, v[176:179], s[18:19] offset:256
	v_add_u32_e32 v206, 0x8000, v206
	s_waitcnt vmcnt(14)
; __device__ __forceinline__ unsigned cvt_pk_bf16(float lo, float hi) { unsigned r; asm volatile("v_cvt_pk_bf16_f32 %0, %1, %2" : "=v"(r) : "v"(lo), "v"(hi)); return r; }
;     __device__ __forceinline__ void operator()(const f32x4 (&acc)[2][2][4][2], const Unit& u, int wr, int wc, int fr, int fq) const {
;     ...
;                 for (int bj = 0; bj < 2; ++bj) { const u32x4 b = bb[ai][m][bj];
;                     const f32x4 v0 = acc[ai][bj][m][0] + (f32x4){bflo(b.x), bfhi(b.x), bflo(b.y), bfhi(b.y)}, v1 = acc[ai][bj][m][1] + (f32x4){bflo(b.z), bfhi(b.z), bflo(b.w), bfhi(b.w)};
;                     u32x4 w; w.x = cvt_pk_bf16(v0[0], v0[1]); w.y = cvt_pk_bf16(v0[2], v0[3]); w.z = cvt_pk_bf16(v1[0], v1[1]); w.w = cvt_pk_bf16(v1[2], v1[3]);
;                     *(u32x4*)(xb + off + bj * HALF) = w;
;                     const float r0 = bflo(w.x), r1 = bfhi(w.x), r2 = bflo(w.y), r3 = bfhi(w.y), r4 = bflo(w.z), r5 = bfhi(w.z), r6 = bflo(w.w), r7 = bfhi(w.w);
;                     sq += ((r0 * r0 + r1 * r1) + (r2 * r2 + r3 * r3)) + ((r4 * r4 + r5 * r5) + (r6 * r6 + r7 * r7)); }
;                 sq += __shfl_xor(sq, 16); sq += __shfl_xor(sq, 32);
;                 if (fq == 0) part[(ai * HALF + wr * 64 + m * 16 + fr) * 4 + wc] = sq; }
	v_lshlrev_b32_e32 v208, 16, v180
	v_and_b32_e32 v209, s4, v180
	v_pk_add_f32 v[32:33], v[32:33], v[208:209]
	v_cvt_pk_bf16_f32 v180, v32, v33
	v_lshlrev_b32_e32 v212, 16, v180
	v_and_b32_e32 v213, s4, v180
	v_pk_fma_f32 v[192:193], v[212:213], v[212:213], v[192:193]
	v_lshlrev_b32_e32 v210, 16, v181
	v_and_b32_e32 v211, s4, v181
	v_pk_add_f32 v[34:35], v[34:35], v[210:211]
	v_cvt_pk_bf16_f32 v181, v34, v35
	v_lshlrev_b32_e32 v214, 16, v181
	v_and_b32_e32 v215, s4, v181
	v_pk_fma_f32 v[192:193], v[214:215], v[214:215], v[192:193]
	v_lshlrev_b32_e32 v208, 16, v182
	v_and_b32_e32 v209, s4, v182
	v_pk_add_f32 v[28:29], v[28:29], v[208:209]
	v_cvt_pk_bf16_f32 v182, v28, v29
	v_lshlrev_b32_e32 v212, 16, v182
	v_and_b32_e32 v213, s4, v182
	v_pk_fma_f32 v[192:193], v[212:213], v[212:213], v[192:193]
	v_lshlrev_b32_e32 v210, 16, v183
	v_and_b32_e32 v211, s4, v183
	v_pk_add_f32 v[30:31], v[30:31], v[210:211]
	v_cvt_pk_bf16_f32 v183, v30, v31
	v_lshlrev_b32_e32 v214, 16, v183
	v_and_b32_e32 v215, s4, v183
	v_pk_fma_f32 v[192:193], v[214:215], v[214:215], v[192:193]
	global_store_dwordx4 v206, v[180:183], s[18:19]
	v_lshlrev_b32_e32 v208, 16, v184
	v_and_b32_e32 v209, s4, v184
	v_pk_add_f32 v[24:25], v[24:25], v[208:209]
	v_cvt_pk_bf16_f32 v184, v24, v25
	v_lshlrev_b32_e32 v212, 16, v184
	v_and_b32_e32 v213, s4, v184
	v_pk_fma_f32 v[192:193], v[212:213], v[212:213], v[192:193]
	v_lshlrev_b32_e32 v210, 16, v185
	v_and_b32_e32 v211, s4, v185
	v_pk_add_f32 v[26:27], v[26:27], v[210:211]
	v_cvt_pk_bf16_f32 v185, v26, v27
	v_lshlrev_b32_e32 v214, 16, v185
	v_and_b32_e32 v215, s4, v185
	v_pk_fma_f32 v[192:193], v[214:215], v[214:215], v[192:193]
	v_lshlrev_b32_e32 v208, 16, v186
	v_and_b32_e32 v209, s4, v186
	v_pk_add_f32 v[20:21], v[20:21], v[208:209]
	v_cvt_pk_bf16_f32 v186, v20, v21
	v_lshlrev_b32_e32 v212, 16, v186
	v_and_b32_e32 v213, s4, v186
	v_pk_fma_f32 v[192:193], v[212:213], v[212:213], v[192:193]
	v_lshlrev_b32_e32 v210, 16, v187
	v_and_b32_e32 v211, s4, v187
	v_pk_add_f32 v[22:23], v[22:23], v[210:211]
	v_cvt_pk_bf16_f32 v187, v22, v23
	v_lshlrev_b32_e32 v214, 16, v187
	v_and_b32_e32 v215, s4, v187
	v_pk_fma_f32 v[192:193], v[214:215], v[214:215], v[192:193]
	global_store_dwordx4 v206, v[184:187], s[18:19] offset:256
	v_add_u32_e32 v206, 0x8000, v206
	s_waitcnt vmcnt(14)
	v_lshlrev_b32_e32 v208, 16, v188
	v_and_b32_e32 v209, s4, v188
	v_pk_add_f32 v[16:17], v[16:17], v[208:209]
	v_cvt_pk_bf16_f32 v188, v16, v17
	v_lshlrev_b32_e32 v212, 16, v188
	v_and_b32_e32 v213, s4, v188
	v_pk_fma_f32 v[172:173], v[212:213], v[212:213], v[172:173]
	v_lshlrev_b32_e32 v210, 16, v189
	v_and_b32_e32 v211, s4, v189
	v_pk_add_f32 v[18:19], v[18:19], v[210:211]
	v_cvt_pk_bf16_f32 v189, v18, v19
	v_lshlrev_b32_e32 v214, 16, v189
	v_and_b32_e32 v215, s4, v189
	v_pk_fma_f32 v[172:173], v[214:215], v[214:215], v[172:173]
	v_lshlrev_b32_e32 v208, 16, v190
	v_and_b32_e32 v209, s4, v190
	v_pk_add_f32 v[12:13], v[12:13], v[208:209]
	v_cvt_pk_bf16_f32 v190, v12, v13
	v_lshlrev_b32_e32 v212, 16, v190
	v_and_b32_e32 v213, s4, v190
	v_pk_fma_f32 v[172:173], v[212:213], v[212:213], v[172:173]
	v_lshlrev_b32_e32 v210, 16, v191
	v_and_b32_e32 v211, s4, v191
	v_pk_add_f32 v[14:15], v[14:15], v[210:211]
	v_cvt_pk_bf16_f32 v191, v14, v15
	v_lshlrev_b32_e32 v214, 16, v191
	v_and_b32_e32 v215, s4, v191
	v_pk_fma_f32 v[172:173], v[214:215], v[214:215], v[172:173]
	global_store_dwordx4 v206, v[188:191], s[18:19]
	v_lshlrev_b32_e32 v208, 16, v202
	v_and_b32_e32 v209, s4, v202
	v_pk_add_f32 v[8:9], v[8:9], v[208:209]
	v_cvt_pk_bf16_f32 v202, v8, v9
	v_lshlrev_b32_e32 v212, 16, v202
	v_and_b32_e32 v213, s4, v202
	v_pk_fma_f32 v[172:173], v[212:213], v[212:213], v[172:173]
	v_lshlrev_b32_e32 v210, 16, v203
	v_and_b32_e32 v211, s4, v203
	v_pk_add_f32 v[10:11], v[10:11], v[210:211]
	v_cvt_pk_bf16_f32 v203, v10, v11
	v_lshlrev_b32_e32 v214, 16, v203
	v_and_b32_e32 v215, s4, v203
	v_pk_fma_f32 v[172:173], v[214:215], v[214:215], v[172:173]
	v_lshlrev_b32_e32 v208, 16, v204
	v_and_b32_e32 v209, s4, v204
	v_pk_add_f32 v[4:5], v[4:5], v[208:209]
	v_cvt_pk_bf16_f32 v204, v4, v5
	v_lshlrev_b32_e32 v212, 16, v204
	v_and_b32_e32 v213, s4, v204
	v_pk_fma_f32 v[172:173], v[212:213], v[212:213], v[172:173]
	v_lshlrev_b32_e32 v210, 16, v205
	v_and_b32_e32 v211, s4, v205
	v_pk_add_f32 v[6:7], v[6:7], v[210:211]
	v_cvt_pk_bf16_f32 v205, v6, v7
	v_lshlrev_b32_e32 v214, 16, v205
	v_and_b32_e32 v215, s4, v205
	v_pk_fma_f32 v[172:173], v[214:215], v[214:215], v[172:173]
	global_store_dwordx4 v206, v[202:205], s[18:19] offset:256
	v_add_f32_e32 v216, v216, v217
	v_add_f32_e32 v218, v218, v219
	v_add_f32_e32 v248, v248, v249
	v_add_f32_e32 v250, v250, v251
	v_add_f32_e32 v252, v252, v253
	v_add_f32_e32 v2, v2, v3
	v_add_f32_e32 v192, v192, v193
	v_add_f32_e32 v172, v172, v173
	v_xor_b32_e32 v174, 16, v226
	v_xor_b32_e32 v175, 32, v226
	v_lshlrev_b32_e32 v174, 2, v174
	v_lshlrev_b32_e32 v175, 2, v175
	ds_bpermute_b32 v168, v174, v216
	ds_bpermute_b32 v169, v174, v218
	ds_bpermute_b32 v170, v174, v248
	ds_bpermute_b32 v171, v174, v250
	ds_bpermute_b32 v140, v174, v252
	ds_bpermute_b32 v141, v174, v2
	ds_bpermute_b32 v142, v174, v192
	ds_bpermute_b32 v143, v174, v172
	s_waitcnt lgkmcnt(0)
	v_add_f32_e32 v216, v216, v168
	v_add_f32_e32 v218, v218, v169
	v_add_f32_e32 v248, v248, v170
	v_add_f32_e32 v250, v250, v171
	v_add_f32_e32 v252, v252, v140
	v_add_f32_e32 v2, v2, v141
	v_add_f32_e32 v192, v192, v142
	v_add_f32_e32 v172, v172, v143
	ds_bpermute_b32 v168, v175, v216
	ds_bpermute_b32 v169, v175, v218
	ds_bpermute_b32 v170, v175, v248
	ds_bpermute_b32 v171, v175, v250
	ds_bpermute_b32 v140, v175, v252
	ds_bpermute_b32 v141, v175, v2
	ds_bpermute_b32 v142, v175, v192
	ds_bpermute_b32 v143, v175, v172
	s_waitcnt lgkmcnt(0)
	v_add_f32_e32 v216, v216, v168
	v_add_f32_e32 v218, v218, v169
	v_add_f32_e32 v248, v248, v170
	v_add_f32_e32 v250, v250, v171
	v_add_f32_e32 v252, v252, v140
	v_add_f32_e32 v2, v2, v141
	v_add_f32_e32 v192, v192, v142
	v_add_f32_e32 v172, v172, v143
	s_and_saveexec_b64 s[4:5], s[6:7]
	ds_write_b32 v246, v216
	ds_write_b32 v246, v218 offset:256
	ds_write_b32 v246, v248 offset:512
	ds_write_b32 v246, v250 offset:768
	ds_write_b32 v246, v252 offset:2048
	ds_write_b32 v246, v2 offset:2304
	ds_write_b32 v246, v192 offset:2560
	ds_write_b32 v246, v172 offset:2816
